# prio
# baseline (speedup 1.0000x reference)
; __device__ __forceinline__ void attn_passes(const Params& p, LAS unsigned char* lds) {
;     ...
;     const int tid = threadIdx.x, w = __builtin_amdgcn_readfirstlane(tid >> 6), lane = tid & 63, qi = lane & 15, g = lane >> 4;
.Lpq_skip:
	s_lshr_b32 s101, s8, 8
	s_cmp_eq_u32 s101, 0
	s_cbranch_scc1 .Lat_prio_done
	s_setprio 1

; #define AT_WAITV(n) asm volatile("s_waitcnt vmcnt(" #n ")" ::: "memory")
; #define AT_BAR() do { asm volatile("" ::: "memory"); __builtin_amdgcn_s_barrier(); asm volatile("" ::: "memory"); } while (0)
; __device__ __forceinline__ void attn_passes(const Params& p, LAS unsigned char* lds) {
;     ...
;     AT_WAITV(0); AT_BAR();
; }
; __global__ void __launch_bounds__(NTHREADS, 2) fwd_megakernel(Params p) {
;     ...
;     if (threadIdx.x == 0) { bst[0] = 0u; bst[1] = 0u; }
.LBB0_316:
	s_setprio 0
	s_waitcnt vmcnt(0)
	s_barrier
	s_and_saveexec_b64 s[4:5], s[14:15]
	s_cbranch_execz .LBB0_318
	s_add_i32 s6, 0, 0x20000
	v_mov_b32_e32 v0, 0
	v_mov_b32_e32 v1, s6
	s_add_i32 s6, 0, 0x20004
	ds_write_b32 v1, v0
	v_mov_b32_e32 v1, s6
	ds_write_b32 v1, v0
